# stagger of the XCD groups doubled (g x ~7 us)
# baseline (speedup 1.0000x reference)
; __device__ __forceinline__ void xcd_barrier(const XcdBarrier& b) {
;     ...
;     __syncthreads();
; __global__ void __launch_bounds__(NWAVES * 64, 2) fwd_kernel(Args args) {
;     ...
;         if (ph + 1 < args.ph_hi || rep + 1 < nrep) { if (args.ph_hi > 1000) grid.sync(); else xcd_barrier(xb); } else __syncthreads();
.LBB0_486:
	s_or_b64 exec, exec, s[26:27]
	s_cmp_eq_u32 s10, 1
	s_cbranch_scc0 stg_skip
	s_and_b32 s2, s89, 7
	s_lshl_b32 s2, s2, 1
